# attention MLA/MoBA: next-tile LDS stores issued before the second PV MFMA group (overlap LDS writes with MFMAs)
# baseline (speedup 1.0000x reference)
; __device__ __forceinline__ unsigned cvt_pk_bf16(float lo, float hi) { unsigned r; asm volatile("v_cvt_pk_bf16_f32 %0, %1, %2" : "=v"(r) : "v"(lo), "v"(hi)); return r; }
; __device__ __forceinline__ float fast_exp2(float x) { return __builtin_amdgcn_exp2f(x); }
; template <int DQ, int TYPE>
; __device__ __forceinline__ void attn_item(PP p, int layer, int b, int h, int qt, char* lds, const int tid_, unsigned* next_ctr, volatile XLAS unsigned* slot) {
;     ...
;             const float m_old_ = m_run;
;             const float mnew = fmaxf(m_run, mx);
;             const float alpha = fast_exp2(m_run - mnew);
;             m_run = mnew;
;             float ls = 0.f;
; #pragma unroll
;             for (int i = 0; i < 16; ++i) { sacc[i] = fast_exp2(__builtin_fmaf(sacc[i], c, -mnew)); ls += sacc[i]; }
;             l_run = l_run * alpha + ls;
;             if (__builtin_amdgcn_ballot_w64(mx > m_old_) != 0) {
; #pragma unroll
;                 for (int md = 0; md < 4; ++md) O[md] *= alpha;
;             }
; #pragma unroll
;             for (int s2 = 0; s2 < 2; ++s2) {
;                 if (s2 == 0) {
; #pragma unroll
;                     for (int md = 0; md < 4; ++md) { vf[1][md][0] = *(const u32x2*)(vb0 + 16 + md * 32 * VLD); vf[1][md][1] = *(const u32x2*)(vb0 + 16 + md * 32 * VLD + 8); }
;                 }
;                 u32x4 pb;
;                 pb.x = cvt_pk_bf16(sacc[8 * s2 + 0], sacc[8 * s2 + 1]); pb.y = cvt_pk_bf16(sacc[8 * s2 + 2], sacc[8 * s2 + 3]);
;                 pb.z = cvt_pk_bf16(sacc[8 * s2 + 4], sacc[8 * s2 + 5]); pb.w = cvt_pk_bf16(sacc[8 * s2 + 6], sacc[8 * s2 + 7]);
;                 const bf16x8 bfrag = __builtin_bit_cast(bf16x8, pb);
;                 __builtin_amdgcn_sched_barrier(0);
; #pragma unroll
;                 for (int md = 0; md < 4; ++md) {
;                     u32x4 av; av.x = vf[s2][md][0].x; av.y = vf[s2][md][0].y; av.z = vf[s2][md][1].x; av.w = vf[s2][md][1].y;
;                     O[md] = __builtin_amdgcn_mfma_f32_32x32x16_bf16(__builtin_bit_cast(bf16x8, av), bfrag, O[md], 0, 0, 0);
;                 }
;                 __builtin_amdgcn_sched_barrier(0);
;             }
;         }
;         if (j < j_hi) A_LSTORE(A, buf ^ 1);
.LBB0_645:
	v_fma_f32 v66, v66, s33, -v165
	v_exp_f32_e32 v176, v66
	v_fma_f32 v66, v67, s33, -v165
	v_exp_f32_e32 v177, v66
	v_fma_f32 v66, v68, s33, -v165
	v_exp_f32_e32 v187, v66
	v_fma_f32 v66, v69, s33, -v165
	v_exp_f32_e32 v189, v66
	v_fma_f32 v67, v70, s33, -v165
	v_add_f32_e32 v66, 0, v176
	v_exp_f32_e32 v190, v67
	v_fma_f32 v67, v71, s33, -v165
	v_add_f32_e32 v66, v177, v66
	v_exp_f32_e32 v191, v67
	v_fma_f32 v67, v72, s33, -v165
	v_add_f32_e32 v66, v187, v66
	v_exp_f32_e32 v192, v67
	v_fma_f32 v67, v73, s33, -v165
	v_add_f32_e32 v66, v189, v66
	v_exp_f32_e32 v193, v67
	v_fma_f32 v67, v74, s33, -v165
	v_add_f32_e32 v66, v190, v66
	v_exp_f32_e32 v194, v67
	v_fma_f32 v67, v75, s33, -v165
	v_add_f32_e32 v66, v191, v66
	v_exp_f32_e32 v195, v67
	v_fma_f32 v67, v76, s33, -v165
	v_add_f32_e32 v66, v192, v66
	v_exp_f32_e32 v196, v67
	v_fma_f32 v67, v77, s33, -v165
	v_add_f32_e32 v66, v193, v66
	v_exp_f32_e32 v197, v67
	v_fma_f32 v67, v78, s33, -v165
	v_add_f32_e32 v66, v194, v66
	v_exp_f32_e32 v198, v67
	v_fma_f32 v67, v79, s33, -v165
	v_add_f32_e32 v66, v195, v66
	v_exp_f32_e32 v199, v67
	v_fma_f32 v67, v80, s33, -v165
	v_add_f32_e32 v66, v196, v66
	v_exp_f32_e32 v200, v67
	v_fma_f32 v67, v81, s33, -v165
	v_add_f32_e32 v66, v197, v66
	v_exp_f32_e32 v201, v67
	v_add_f32_e32 v66, v198, v66
	v_add_f32_e32 v66, v199, v66
	v_add_f32_e32 v66, v200, v66
	v_add_f32_e32 v202, v201, v66
	ds_read2_b64 v[66:69], v173 offset0:132 offset1:134
	ds_read2_b64 v[70:73], v175 offset0:164 offset1:166
	ds_read2_b64 v[74:77], v174 offset0:196 offset1:198
	ds_read2_b64 v[78:81], v172 offset0:228 offset1:230
	v_fmac_f32_e32 v202, v164, v152
	v_cvt_pk_bf16_f32 v172, v176, v177
	v_cvt_pk_bf16_f32 v173, v187, v189
	v_cvt_pk_bf16_f32 v174, v190, v191
	v_cvt_pk_bf16_f32 v175, v192, v193
	s_waitcnt lgkmcnt(4)
	s_nop 0
	v_mfma_f32_32x32x16_bf16 v[18:33], v[142:145], v[172:175], v[18:33]
	v_mfma_f32_32x32x16_bf16 v[2:17], v[138:141], v[172:175], v[2:17]
	v_mfma_f32_32x32x16_bf16 v[50:65], v[134:137], v[172:175], v[50:65]
	v_mfma_f32_32x32x16_bf16 v[34:49], v[130:133], v[172:175], v[34:49]
	s_andn2_b64 vcc, exec, s[12:13]
	s_cbranch_vccnz .Lnolst_moba
	s_xor_b32 s32, s63, 1
	s_mul_i32 s32, s32, 0x8f70
	s_add_i32 s32, s32, 16
	v_lshl_add_u32 v244, v185, 1, s32
	v_add_u32_e32 v245, v244, v158
	v_add_u32_e32 v244, v244, v159
	s_waitcnt vmcnt(3)
	ds_write_b128 v245, v[82:85]
	s_waitcnt vmcnt(2)
	ds_write_b128 v244, v[86:89]
	s_waitcnt vmcnt(1)
	v_and_b32_e32 v244, 0xffff, v106
	v_add3_u32 v245, s32, v161, v160
	v_lshrrev_b32_e32 v246, 16, v106
	s_waitcnt vmcnt(0)
	v_lshl_or_b32 v244, v118, 16, v244
	v_and_or_b32 v246, v118, s91, v246
	v_add_u32_e32 v245, 0x4400, v245
	ds_write_b32 v245, v244
	ds_write_b32 v245, v246 offset:2448
	v_and_b32_e32 v244, 0xffff, v107
	v_lshrrev_b32_e32 v246, 16, v107
	v_lshl_or_b32 v244, v119, 16, v244
	v_and_or_b32 v246, v119, s91, v246
	ds_write_b32 v245, v244 offset:4896
	ds_write_b32 v245, v246 offset:7344
	v_and_b32_e32 v244, 0xffff, v108
	v_lshrrev_b32_e32 v246, 16, v108
	v_lshl_or_b32 v244, v120, 16, v244
	v_and_or_b32 v246, v120, s91, v246
	ds_write_b32 v245, v244 offset:9792
	ds_write_b32 v245, v246 offset:12240
	v_and_b32_e32 v244, 0xffff, v109
	v_lshrrev_b32_e32 v246, 16, v109
	v_lshl_or_b32 v244, v121, 16, v244
	v_and_or_b32 v246, v121, s91, v246
	ds_write_b32 v245, v244 offset:14688
	ds_write_b32 v245, v246 offset:17136
	v_cvt_pk_bf16_f32 v130, v194, v195
	v_cvt_pk_bf16_f32 v131, v196, v197
	v_cvt_pk_bf16_f32 v132, v198, v199
	v_cvt_pk_bf16_f32 v133, v200, v201
	s_waitcnt lgkmcnt(13)
	v_mfma_f32_32x32x16_bf16 v[18:33], v[66:69], v[130:133], v[18:33]
	s_waitcnt lgkmcnt(12)
	v_mfma_f32_32x32x16_bf16 v[2:17], v[70:73], v[130:133], v[2:17]
	s_waitcnt lgkmcnt(11)
	v_mfma_f32_32x32x16_bf16 v[50:65], v[74:77], v[130:133], v[50:65]
	s_waitcnt lgkmcnt(10)
	v_mfma_f32_32x32x16_bf16 v[34:49], v[78:81], v[130:133], v[34:49]
	v_mov_b32_e32 v164, v202
	s_branch .LBB0_648
.Lnolst_moba:
	v_cvt_pk_bf16_f32 v130, v194, v195
	v_cvt_pk_bf16_f32 v131, v196, v197
	v_cvt_pk_bf16_f32 v132, v198, v199
	v_cvt_pk_bf16_f32 v133, v200, v201
	s_waitcnt lgkmcnt(3)
	v_mfma_f32_32x32x16_bf16 v[18:33], v[66:69], v[130:133], v[18:33]
	s_waitcnt lgkmcnt(2)
	v_mfma_f32_32x32x16_bf16 v[2:17], v[70:73], v[130:133], v[2:17]
	s_waitcnt lgkmcnt(1)
	v_mfma_f32_32x32x16_bf16 v[50:65], v[74:77], v[130:133], v[50:65]
	s_waitcnt lgkmcnt(0)
	v_mfma_f32_32x32x16_bf16 v[34:49], v[78:81], v[130:133], v[34:49]
	v_mov_b32_e32 v164, v202
	s_branch .LBB0_648

; __device__ __forceinline__ unsigned cvt_pk_bf16(float lo, float hi) { unsigned r; asm volatile("v_cvt_pk_bf16_f32 %0, %1, %2" : "=v"(r) : "v"(lo), "v"(hi)); return r; }
; __device__ __forceinline__ float fast_exp2(float x) { return __builtin_amdgcn_exp2f(x); }
; template <int DQ, int TYPE>
; __device__ __forceinline__ void attn_item(PP p, int layer, int b, int h, int qt, char* lds, const int tid_, unsigned* next_ctr, volatile XLAS unsigned* slot) {
;     ...
;             const float m_old_ = m_run;
;             const float mnew = fmaxf(m_run, mx);
;             const float alpha = fast_exp2(m_run - mnew);
;             m_run = mnew;
;             float ls = 0.f;
; #pragma unroll
;             for (int i = 0; i < 16; ++i) { sacc[i] = fast_exp2(__builtin_fmaf(sacc[i], c, -mnew)); ls += sacc[i]; }
;             l_run = l_run * alpha + ls;
;             if (__builtin_amdgcn_ballot_w64(mx > m_old_) != 0) {
; #pragma unroll
;                 for (int md = 0; md < 4; ++md) O[md] *= alpha;
;             }
; #pragma unroll
;             for (int s2 = 0; s2 < 2; ++s2) {
;                 if (s2 == 0) {
; #pragma unroll
;                     for (int md = 0; md < 4; ++md) { vf[1][md][0] = *(const u32x2*)(vb0 + 16 + md * 32 * VLD); vf[1][md][1] = *(const u32x2*)(vb0 + 16 + md * 32 * VLD + 8); }
;                 }
;                 u32x4 pb;
;                 pb.x = cvt_pk_bf16(sacc[8 * s2 + 0], sacc[8 * s2 + 1]); pb.y = cvt_pk_bf16(sacc[8 * s2 + 2], sacc[8 * s2 + 3]);
;                 pb.z = cvt_pk_bf16(sacc[8 * s2 + 4], sacc[8 * s2 + 5]); pb.w = cvt_pk_bf16(sacc[8 * s2 + 6], sacc[8 * s2 + 7]);
;                 const bf16x8 bfrag = __builtin_bit_cast(bf16x8, pb);
;                 __builtin_amdgcn_sched_barrier(0);
; #pragma unroll
;                 for (int md = 0; md < 4; ++md) {
;                     u32x4 av; av.x = vf[s2][md][0].x; av.y = vf[s2][md][0].y; av.z = vf[s2][md][1].x; av.w = vf[s2][md][1].y;
;                     O[md] = __builtin_amdgcn_mfma_f32_32x32x16_bf16(__builtin_bit_cast(bf16x8, av), bfrag, O[md], 0, 0, 0);
;                 }
;                 __builtin_amdgcn_sched_barrier(0);
;             }
;         }
;         if (j < j_hi) A_LSTORE(A, buf ^ 1);
.LBB0_669:
	v_fma_f32 v66, v66, s86, -v200
	v_exp_f32_e32 v205, v66
	v_fma_f32 v66, v67, s86, -v200
	v_exp_f32_e32 v206, v66
	v_fma_f32 v66, v68, s86, -v200
	v_exp_f32_e32 v207, v66
	v_fma_f32 v66, v69, s86, -v200
	v_exp_f32_e32 v208, v66
	v_fma_f32 v67, v70, s86, -v200
	v_add_f32_e32 v66, 0, v205
	v_exp_f32_e32 v209, v67
	v_fma_f32 v67, v71, s86, -v200
	v_add_f32_e32 v66, v206, v66
	v_exp_f32_e32 v210, v67
	v_fma_f32 v67, v72, s86, -v200
	v_add_f32_e32 v66, v207, v66
	v_exp_f32_e32 v211, v67
	v_fma_f32 v67, v73, s86, -v200
	v_add_f32_e32 v66, v208, v66
	v_exp_f32_e32 v212, v67
	v_fma_f32 v67, v74, s86, -v200
	v_add_f32_e32 v66, v209, v66
	v_exp_f32_e32 v213, v67
	v_fma_f32 v67, v75, s86, -v200
	v_add_f32_e32 v66, v210, v66
	v_exp_f32_e32 v214, v67
	v_fma_f32 v67, v76, s86, -v200
	v_add_f32_e32 v66, v211, v66
	v_exp_f32_e32 v215, v67
	v_fma_f32 v67, v77, s86, -v200
	v_add_f32_e32 v66, v212, v66
	v_exp_f32_e32 v216, v67
	v_fma_f32 v67, v78, s86, -v200
	v_add_f32_e32 v66, v213, v66
	v_exp_f32_e32 v217, v67
	v_fma_f32 v67, v79, s86, -v200
	v_add_f32_e32 v66, v214, v66
	v_exp_f32_e32 v218, v67
	v_fma_f32 v67, v80, s86, -v200
	v_add_f32_e32 v66, v215, v66
	v_exp_f32_e32 v219, v67
	v_fma_f32 v67, v81, s86, -v200
	v_add_f32_e32 v66, v216, v66
	v_exp_f32_e32 v230, v67
	v_add_f32_e32 v66, v217, v66
	v_add_f32_e32 v66, v218, v66
	v_add_f32_e32 v66, v219, v66
	v_add_f32_e32 v231, v230, v66
	ds_read2_b64 v[66:69], v203 offset0:132 offset1:134
	ds_read2_b64 v[70:73], v201 offset0:164 offset1:166
	ds_read2_b64 v[74:77], v204 offset0:196 offset1:198
	ds_read2_b64 v[78:81], v202 offset0:228 offset1:230
	v_fmac_f32_e32 v231, v199, v192
	v_cvt_pk_bf16_f32 v202, v205, v206
	v_cvt_pk_bf16_f32 v203, v207, v208
	v_cvt_pk_bf16_f32 v204, v209, v210
	v_cvt_pk_bf16_f32 v205, v211, v212
	s_waitcnt lgkmcnt(4)
	s_nop 0
	v_mfma_f32_32x32x16_bf16 v[18:33], v[162:165], v[202:205], v[18:33]
	v_mfma_f32_32x32x16_bf16 v[2:17], v[158:161], v[202:205], v[2:17]
	v_mfma_f32_32x32x16_bf16 v[50:65], v[154:157], v[202:205], v[50:65]
	v_mfma_f32_32x32x16_bf16 v[34:49], v[150:153], v[202:205], v[34:49]
	s_andn2_b64 vcc, exec, s[12:13]
	s_cbranch_vccnz .Lnolst_mla
	s_xor_b32 s32, s58, 1
	s_mul_i32 s32, s32, 0xaf70
	s_add_i32 s32, s32, 16
	v_lshl_add_u32 v244, v185, 1, s32
	v_add_u32_e32 v245, v244, v189
	v_add_u32_e32 v244, v244, v193
	s_waitcnt vmcnt(4)
	ds_write_b128 v245, v[86:89]
	s_waitcnt vmcnt(3)
	ds_write_b128 v244, v[90:93]
	v_add3_u32 v244, s32, v194, v0
	v_lshlrev_b32_e32 v245, 1, v170
	s_waitcnt vmcnt(2)
	ds_write_b128 v244, v[118:121] offset:256
	s_waitcnt vmcnt(1)
	v_and_b32_e32 v244, 0xffff, v114
	v_add3_u32 v245, s32, v195, v245
	v_lshrrev_b32_e32 v246, 16, v114
	s_waitcnt vmcnt(0)
	v_lshl_or_b32 v244, v122, 16, v244
	v_and_or_b32 v246, v122, s91, v246
	v_add_u32_e32 v245, 0x6400, v245
	ds_write_b32 v245, v244
	ds_write_b32 v245, v246 offset:2448
	v_and_b32_e32 v244, 0xffff, v115
	v_lshrrev_b32_e32 v246, 16, v115
	v_lshl_or_b32 v244, v123, 16, v244
	v_and_or_b32 v246, v123, s91, v246
	ds_write_b32 v245, v244 offset:4896
	ds_write_b32 v245, v246 offset:7344
	v_and_b32_e32 v244, 0xffff, v116
	v_lshrrev_b32_e32 v246, 16, v116
	v_lshl_or_b32 v244, v124, 16, v244
	v_and_or_b32 v246, v124, s91, v246
	ds_write_b32 v245, v244 offset:9792
	ds_write_b32 v245, v246 offset:12240
	v_and_b32_e32 v244, 0xffff, v117
	v_lshrrev_b32_e32 v246, 16, v117
	v_lshl_or_b32 v244, v125, 16, v244
	v_and_or_b32 v246, v125, s91, v246
	ds_write_b32 v245, v244 offset:14688
	ds_write_b32 v245, v246 offset:17136
	v_cvt_pk_bf16_f32 v150, v213, v214
	v_cvt_pk_bf16_f32 v151, v215, v216
	v_cvt_pk_bf16_f32 v152, v217, v218
	v_cvt_pk_bf16_f32 v153, v219, v230
	s_waitcnt lgkmcnt(14)
	v_mfma_f32_32x32x16_bf16 v[18:33], v[66:69], v[150:153], v[18:33]
	s_waitcnt lgkmcnt(13)
	v_mfma_f32_32x32x16_bf16 v[2:17], v[70:73], v[150:153], v[2:17]
	s_waitcnt lgkmcnt(12)
	v_mfma_f32_32x32x16_bf16 v[50:65], v[74:77], v[150:153], v[50:65]
	s_waitcnt lgkmcnt(11)
	v_mfma_f32_32x32x16_bf16 v[34:49], v[78:81], v[150:153], v[34:49]
	v_mov_b32_e32 v199, v231
	s_branch .LBB0_672
.Lnolst_mla:
	v_cvt_pk_bf16_f32 v150, v213, v214
	v_cvt_pk_bf16_f32 v151, v215, v216
	v_cvt_pk_bf16_f32 v152, v217, v218
	v_cvt_pk_bf16_f32 v153, v219, v230
	s_waitcnt lgkmcnt(3)
	v_mfma_f32_32x32x16_bf16 v[18:33], v[66:69], v[150:153], v[18:33]
	s_waitcnt lgkmcnt(2)
	v_mfma_f32_32x32x16_bf16 v[2:17], v[70:73], v[150:153], v[2:17]
	s_waitcnt lgkmcnt(1)
	v_mfma_f32_32x32x16_bf16 v[50:65], v[74:77], v[150:153], v[50:65]
	s_waitcnt lgkmcnt(0)
	v_mfma_f32_32x32x16_bf16 v[34:49], v[78:81], v[150:153], v[34:49]
	v_mov_b32_e32 v199, v231
	s_branch .LBB0_672
